# p2align 6 on the remaining inner loop heads (LN, gla_post, prep, gMLP, attention KV loop) on top of v112
# speedup vs baseline: 1.0006x; 1.0006x over previous
.LBB0_190:
	s_or_b64 exec, exec, s[8:9]
	v_readlane_b32 s1, v255, 3
	s_waitcnt lgkmcnt(0)
	s_barrier
	v_mov_b32_e32 v0, s1
	ds_read_b32 v0, v0
	s_movk_i32 s8, 0x37f
	s_waitcnt lgkmcnt(0)
	v_cmp_lt_i32_e32 vcc, s8, v0
	v_readfirstlane_b32 s1, v0
	s_mov_b64 s[8:9], -1
	s_cbranch_vccnz .LBB0_185
	s_cmpk_gt_i32 s1, 0x7f
	s_cbranch_scc0 .LBB0_242
	s_cmpk_gt_u32 s1, 0x27f
	s_cbranch_scc0 .LBB0_202
	v_mov_b32_e32 v2, v163
	s_lshl_b32 s9, s1, 7
	v_readfirstlane_b32 s12, v2
	s_ashr_i32 s8, s12, 6
	s_add_i32 s84, s9, 0xfffec000
	s_lshl_b32 s8, s8, 4
	s_and_b32 s9, s12, 0xffffffc0
	s_add_i32 s14, s9, 0
	s_ashr_i32 s9, s8, 31
	s_add_u32 s8, s8, s84
	s_addc_u32 s9, s9, 0
	s_mulk_i32 s9, 0x3400
	s_mul_hi_u32 s10, s8, 0x3400
	s_add_i32 s10, s10, s9
	s_mulk_i32 s8, 0x3400
	v_readlane_b32 s9, v255, 47
	v_and_b32_e32 v3, 63, v2
	s_add_u32 s8, s9, s8
	v_readlane_b32 s9, v255, 48
	v_lshlrev_b32_e32 v0, 2, v3
	v_lshlrev_b32_e32 v128, 4, v3
	s_addc_u32 s9, s9, s10
	s_mov_b32 s13, 0
	v_cmp_eq_u32_e32 vcc, 0, v3
	v_xor_b32_e32 v4, 0x80, v0
	v_xor_b32_e32 v5, 64, v0
	v_xor_b32_e32 v6, 32, v0
	v_xor_b32_e32 v7, 16, v0
	v_xor_b32_e32 v8, 8, v0
	v_xor_b32_e32 v9, 4, v0
	v_lshl_add_u64 v[0:1], s[8:9], 0, v[128:129]
	s_barrier
	s_branch .LBB0_195
	.p2align 6

.LBB0_198:
	s_add_i32 s90, s73, s0
	s_ashr_i32 s91, s90, 31
	s_lshl_b64 s[82:83], s[90:91], 16
	v_lshl_add_u64 v[16:17], v[56:57], 0, s[82:83]
	s_lshl_b32 s82, s73, 8
	s_mov_b32 s83, s85
	v_lshl_add_u64 v[2:3], v[36:37], 0, s[82:83]
	s_lshl_b32 s84, s73, 7
	global_load_dwordx4 v[18:21], v[2:3], off
	s_lshl_b64 s[96:97], s[84:85], 2
	v_lshl_add_u64 v[0:1], v[52:53], 0, s[96:97]
	v_lshl_add_u64 v[8:9], v[54:55], 0, s[96:97]
	ds_read_b32 v22, v71
	ds_read_b32 v23, v72
	global_load_dwordx4 v[4:7], v[0:1], off offset:16
	global_load_dwordx4 v[12:15], v[0:1], off
	s_nop 0
	global_load_dwordx4 v[0:3], v[8:9], off offset:16
	s_nop 0
	global_load_dwordx4 v[8:11], v[8:9], off
	v_mov_b32_e32 v62, v66
	v_mov_b32_e32 v63, v84
	s_waitcnt vmcnt(4)
	v_lshlrev_b32_e32 v24, 16, v18
	v_and_b32_e32 v18, 0xffff0000, v18
	v_lshlrev_b32_e32 v25, 16, v19
	v_and_b32_e32 v19, 0xffff0000, v19
	v_lshlrev_b32_e32 v26, 16, v20
	v_and_b32_e32 v20, 0xffff0000, v20
	v_lshlrev_b32_e32 v27, 16, v21
	v_and_b32_e32 v21, 0xffff0000, v21
	s_waitcnt lgkmcnt(1)
	v_sub_f32_e32 v18, v18, v22
	v_sub_f32_e32 v19, v19, v22
	v_sub_f32_e32 v20, v20, v22
	v_sub_f32_e32 v21, v21, v22
	v_sub_f32_e32 v24, v24, v22
	s_waitcnt lgkmcnt(0)
	v_mul_f32_e32 v18, v23, v18
	v_sub_f32_e32 v25, v25, v22
	v_mul_f32_e32 v19, v23, v19
	v_sub_f32_e32 v26, v26, v22
	v_mul_f32_e32 v20, v23, v20
	v_sub_f32_e32 v27, v27, v22
	v_mul_f32_e32 v21, v23, v21
	v_mul_f32_e32 v24, v23, v24
	s_waitcnt vmcnt(0)
	v_fma_f32 v18, v13, v18, v9
	v_mul_f32_e32 v25, v23, v25
	v_fma_f32 v19, v15, v19, v11
	v_mul_f32_e32 v26, v23, v26
	v_fma_f32 v20, v20, v5, v1
	v_mul_f32_e32 v27, v23, v27
	v_fma_f32 v21, v21, v7, v3
	v_fma_f32 v24, v12, v24, v8
	v_fma_f32 v25, v14, v25, v10
	v_fma_f32 v26, v26, v4, v0
	v_fma_f32 v27, v27, v6, v2
	v_cvt_pk_bf16_f32 v18, v24, v18
	v_cvt_pk_bf16_f32 v19, v25, v19
	v_cvt_pk_bf16_f32 v20, v26, v20
	v_cvt_pk_bf16_f32 v21, v27, v21
	ds_write_b128 v85, v[18:21]
	v_lshl_add_u64 v[22:23], v[38:39], 2, v[16:17]
	global_load_dwordx4 v[18:21], v[22:23], off offset:16
	s_nop 0
	global_load_dwordx4 v[22:25], v[22:23], off
	s_waitcnt vmcnt(1)
	v_cndmask_b32_e64 v26, v18, 0, s[14:15]
	s_waitcnt vmcnt(0)
	v_cndmask_b32_e64 v22, v22, 0, vcc
	v_cndmask_b32_e64 v23, 0, v23, s[8:9]
	v_cndmask_b32_e64 v24, v24, 0, s[10:11]
	v_cndmask_b32_e64 v25, v25, 0, s[12:13]
	v_cndmask_b32_e64 v27, v19, 0, s[16:17]
	v_cndmask_b32_e64 v21, v21, 0, s[20:21]
	v_cvt_pk_bf16_f32 v18, v22, v23
	v_cvt_pk_bf16_f32 v19, v24, v25
	v_cndmask_b32_e64 v28, v20, 0, s[18:19]
	v_cvt_pk_bf16_f32 v20, v26, v27
	v_cvt_pk_bf16_f32 v21, v28, v21
	ds_write_b128 v85, v[18:21] offset:32768
	v_lshl_add_u64 v[18:19], v[40:41], 0, s[82:83]
	global_load_dwordx4 v[18:21], v[18:19], off
	ds_read_b32 v22, v73
	ds_read_b32 v23, v74
	s_waitcnt vmcnt(0)
	v_lshlrev_b32_e32 v24, 16, v18
	v_and_b32_e32 v18, 0xffff0000, v18
	v_lshlrev_b32_e32 v25, 16, v19
	v_and_b32_e32 v19, 0xffff0000, v19
	v_lshlrev_b32_e32 v26, 16, v20
	v_and_b32_e32 v20, 0xffff0000, v20
	v_lshlrev_b32_e32 v27, 16, v21
	v_and_b32_e32 v21, 0xffff0000, v21
	s_waitcnt lgkmcnt(1)
	v_sub_f32_e32 v18, v18, v22
	v_sub_f32_e32 v19, v19, v22
	v_sub_f32_e32 v20, v20, v22
	v_sub_f32_e32 v21, v21, v22
	v_sub_f32_e32 v24, v24, v22
	s_waitcnt lgkmcnt(0)
	v_mul_f32_e32 v18, v23, v18
	v_sub_f32_e32 v25, v25, v22
	v_mul_f32_e32 v19, v23, v19
	v_sub_f32_e32 v26, v26, v22
	v_mul_f32_e32 v20, v23, v20
	v_sub_f32_e32 v27, v27, v22
	v_mul_f32_e32 v21, v23, v21
	v_mul_f32_e32 v24, v23, v24
	v_fma_f32 v18, v13, v18, v9
	v_mul_f32_e32 v25, v23, v25
	v_fma_f32 v19, v15, v19, v11
	v_mul_f32_e32 v26, v23, v26
	v_fma_f32 v20, v5, v20, v1
	v_mul_f32_e32 v27, v23, v27
	v_fma_f32 v21, v7, v21, v3
	v_fma_f32 v24, v12, v24, v8
	v_fma_f32 v25, v14, v25, v10
	v_fma_f32 v26, v4, v26, v0
	v_fma_f32 v27, v6, v27, v2
	v_cvt_pk_bf16_f32 v18, v24, v18
	v_cvt_pk_bf16_f32 v19, v25, v19
	v_cvt_pk_bf16_f32 v20, v26, v20
	v_cvt_pk_bf16_f32 v21, v27, v21
	ds_write_b128 v86, v[18:21]
	v_lshl_add_u64 v[22:23], v[42:43], 2, v[16:17]
	global_load_dwordx4 v[18:21], v[22:23], off offset:16
	s_nop 0
	global_load_dwordx4 v[22:25], v[22:23], off
	s_waitcnt vmcnt(1)
	v_cndmask_b32_e64 v26, v18, 0, s[30:31]
	s_waitcnt vmcnt(0)
	v_cndmask_b32_e64 v22, v22, 0, s[22:23]
	v_cndmask_b32_e64 v23, 0, v23, s[24:25]
	v_cndmask_b32_e64 v24, v24, 0, s[26:27]
	v_cndmask_b32_e64 v25, v25, 0, s[28:29]
	v_cndmask_b32_e64 v27, v19, 0, s[34:35]
	v_cndmask_b32_e64 v21, v21, 0, s[38:39]
	v_cvt_pk_bf16_f32 v18, v22, v23
	v_cvt_pk_bf16_f32 v19, v24, v25
	v_cndmask_b32_e64 v28, v20, 0, s[36:37]
	v_cvt_pk_bf16_f32 v20, v26, v27
	v_cvt_pk_bf16_f32 v21, v28, v21
	ds_write_b128 v86, v[18:21] offset:32768
	v_lshl_add_u64 v[18:19], v[44:45], 0, s[82:83]
	global_load_dwordx4 v[18:21], v[18:19], off
	ds_read_b32 v22, v75
	ds_read_b32 v23, v76
	s_waitcnt vmcnt(0)
	v_lshlrev_b32_e32 v24, 16, v18
	v_and_b32_e32 v18, 0xffff0000, v18
	v_lshlrev_b32_e32 v25, 16, v19
	v_and_b32_e32 v19, 0xffff0000, v19
	v_lshlrev_b32_e32 v26, 16, v20
	v_and_b32_e32 v20, 0xffff0000, v20
	v_lshlrev_b32_e32 v27, 16, v21
	v_and_b32_e32 v21, 0xffff0000, v21
	s_waitcnt lgkmcnt(1)
	v_sub_f32_e32 v18, v18, v22
	v_sub_f32_e32 v19, v19, v22
	v_sub_f32_e32 v20, v20, v22
	v_sub_f32_e32 v21, v21, v22
	v_sub_f32_e32 v24, v24, v22
	s_waitcnt lgkmcnt(0)
	v_mul_f32_e32 v18, v23, v18
	v_sub_f32_e32 v25, v25, v22
	v_mul_f32_e32 v19, v23, v19
	v_sub_f32_e32 v26, v26, v22
	v_mul_f32_e32 v20, v23, v20
	v_sub_f32_e32 v27, v27, v22
	v_mul_f32_e32 v21, v23, v21
	v_mul_f32_e32 v24, v23, v24
	v_fma_f32 v18, v13, v18, v9
	v_mul_f32_e32 v25, v23, v25
	v_fma_f32 v19, v15, v19, v11
	v_mul_f32_e32 v26, v23, v26
	v_fma_f32 v20, v5, v20, v1
	v_mul_f32_e32 v27, v23, v27
	v_fma_f32 v21, v7, v21, v3
	v_fma_f32 v24, v12, v24, v8
	v_fma_f32 v25, v14, v25, v10
	v_fma_f32 v26, v4, v26, v0
	v_fma_f32 v27, v6, v27, v2
	v_cvt_pk_bf16_f32 v18, v24, v18
	v_cvt_pk_bf16_f32 v19, v25, v19
	v_cvt_pk_bf16_f32 v20, v26, v20
	v_cvt_pk_bf16_f32 v21, v27, v21
	ds_write_b128 v87, v[18:21]
	v_lshl_add_u64 v[22:23], v[46:47], 2, v[16:17]
	global_load_dwordx4 v[18:21], v[22:23], off offset:16
	s_nop 0
	global_load_dwordx4 v[22:25], v[22:23], off
	s_waitcnt vmcnt(1)
	v_cndmask_b32_e64 v26, v18, 0, s[48:49]
	s_waitcnt vmcnt(0)
	v_cndmask_b32_e64 v22, v22, 0, s[40:41]
	v_cndmask_b32_e64 v23, 0, v23, s[42:43]
	v_cndmask_b32_e64 v24, v24, 0, s[44:45]
	v_cndmask_b32_e64 v25, v25, 0, s[46:47]
	v_cndmask_b32_e64 v27, v19, 0, s[50:51]
	v_cndmask_b32_e64 v21, v21, 0, s[54:55]
	v_cvt_pk_bf16_f32 v18, v22, v23
	v_cvt_pk_bf16_f32 v19, v24, v25
	v_cndmask_b32_e64 v28, v20, 0, s[52:53]
	v_cvt_pk_bf16_f32 v20, v26, v27
	v_cvt_pk_bf16_f32 v21, v28, v21
	ds_write_b128 v87, v[18:21] offset:32768
	v_lshl_add_u64 v[18:19], v[48:49], 0, s[82:83]
	global_load_dwordx4 v[18:21], v[18:19], off
	ds_read_b32 v22, v77
	ds_read_b32 v23, v78
	s_mov_b32 s82, 0
	s_waitcnt vmcnt(0)
	v_lshlrev_b32_e32 v24, 16, v18
	s_waitcnt lgkmcnt(1)
	v_sub_f32_e32 v24, v24, v22
	v_and_b32_e32 v18, 0xffff0000, v18
	s_waitcnt lgkmcnt(0)
	v_mul_f32_e32 v24, v23, v24
	v_fma_f32 v8, v12, v24, v8
	v_sub_f32_e32 v12, v18, v22
	v_lshlrev_b32_e32 v25, 16, v19
	v_mul_f32_e32 v12, v23, v12
	v_fma_f32 v9, v13, v12, v9
	v_sub_f32_e32 v12, v25, v22
	v_and_b32_e32 v19, 0xffff0000, v19
	v_mul_f32_e32 v12, v23, v12
	v_fma_f32 v10, v14, v12, v10
	v_sub_f32_e32 v12, v19, v22
	v_lshlrev_b32_e32 v26, 16, v20
	v_mul_f32_e32 v12, v23, v12
	v_fmac_f32_e32 v11, v15, v12
	v_sub_f32_e32 v12, v26, v22
	v_and_b32_e32 v20, 0xffff0000, v20
	v_mul_f32_e32 v12, v23, v12
	v_fma_f32 v4, v4, v12, v0
	v_sub_f32_e32 v0, v20, v22
	v_lshlrev_b32_e32 v27, 16, v21
	v_mul_f32_e32 v0, v23, v0
	v_fma_f32 v5, v5, v0, v1
	v_sub_f32_e32 v0, v27, v22
	v_and_b32_e32 v21, 0xffff0000, v21
	v_mul_f32_e32 v0, v23, v0
	v_fma_f32 v6, v6, v0, v2
	v_sub_f32_e32 v0, v21, v22
	v_mul_f32_e32 v0, v23, v0
	v_fmac_f32_e32 v3, v7, v0
	v_cvt_pk_bf16_f32 v0, v8, v9
	v_cvt_pk_bf16_f32 v1, v10, v11
	v_cvt_pk_bf16_f32 v2, v4, v5
	v_cvt_pk_bf16_f32 v3, v6, v3
	ds_write_b128 v88, v[0:3]
	v_lshl_add_u64 v[4:5], v[50:51], 2, v[16:17]
	global_load_dwordx4 v[0:3], v[4:5], off offset:16
	s_nop 0
	global_load_dwordx4 v[4:7], v[4:5], off
	s_waitcnt vmcnt(1)
	v_cndmask_b32_e64 v8, v0, 0, s[64:65]
	s_waitcnt vmcnt(0)
	v_cndmask_b32_e64 v4, v4, 0, s[56:57]
	v_cndmask_b32_e64 v5, 0, v5, s[58:59]
	v_cndmask_b32_e64 v3, v3, 0, s[70:71]
	v_cvt_pk_bf16_f32 v0, v4, v5
	v_cndmask_b32_e64 v6, v6, 0, s[60:61]
	v_cndmask_b32_e64 v7, v7, 0, s[62:63]
	v_cndmask_b32_e64 v9, v1, 0, s[66:67]
	v_cndmask_b32_e64 v10, v2, 0, s[68:69]
	v_cvt_pk_bf16_f32 v1, v6, v7
	v_cvt_pk_bf16_f32 v2, v8, v9
	v_cvt_pk_bf16_f32 v3, v10, v3
	ds_write_b128 v88, v[0:3] offset:32768
	v_mov_b32_e32 v0, 0
	v_mov_b32_e32 v1, v0
	v_mov_b32_e32 v2, v0
	v_mov_b32_e32 v3, v0
	v_mov_b32_e32 v4, v0
	v_mov_b32_e32 v5, v0
	v_mov_b32_e32 v6, v0
	v_mov_b32_e32 v7, v0
	v_mov_b32_e32 v8, v0
	v_mov_b32_e32 v9, v0
	v_mov_b32_e32 v10, v0
	v_mov_b32_e32 v11, v0
	v_mov_b32_e32 v12, v0
	v_mov_b32_e32 v13, v0
	v_mov_b32_e32 v14, v0
	v_mov_b32_e32 v15, v0
	v_mov_b32_e32 v16, v0
	v_mov_b32_e32 v17, v0
	v_mov_b32_e32 v18, v0
	v_mov_b32_e32 v19, v0
	v_mov_b32_e32 v20, v0
	v_mov_b32_e32 v21, v0
	v_mov_b32_e32 v22, v0
	v_mov_b32_e32 v23, v0
	v_mov_b32_e32 v24, v0
	v_mov_b32_e32 v25, v0
	v_mov_b32_e32 v26, v0
	v_mov_b32_e32 v27, v0
	v_mov_b32_e32 v28, v0
	v_mov_b32_e32 v29, v0
	v_mov_b32_e32 v30, v0
	v_mov_b32_e32 v31, v0
	s_waitcnt lgkmcnt(0)
	s_barrier
	.p2align 6

.LBB0_223:
	v_lshl_add_u32 v80, v234, 2, s47
	v_sub_u32_e32 v80, v178, v80
	v_cmp_le_i32_e32 vcc, 0, v80
	s_nop 1
	v_cndmask_b32_e32 v64, v202, v64, vcc
	v_cmp_le_i32_e32 vcc, 1, v80
	s_nop 1
	v_cndmask_b32_e32 v65, v202, v65, vcc
	v_cmp_le_i32_e32 vcc, 2, v80
	s_nop 1
	v_cndmask_b32_e32 v66, v202, v66, vcc
	v_cmp_le_i32_e32 vcc, 3, v80
	s_nop 1
	v_cndmask_b32_e32 v67, v202, v67, vcc
	v_cmp_le_i32_e32 vcc, 8, v80
	s_nop 1
	v_cndmask_b32_e32 v68, v202, v68, vcc
	v_cmp_le_i32_e32 vcc, 9, v80
	s_nop 1
	v_cndmask_b32_e32 v69, v202, v69, vcc
	v_cmp_le_i32_e32 vcc, 10, v80
	s_nop 1
	v_cndmask_b32_e32 v70, v202, v70, vcc
	v_cmp_le_i32_e32 vcc, 11, v80
	s_nop 1
	v_cndmask_b32_e32 v71, v202, v71, vcc
	v_cmp_le_i32_e32 vcc, 16, v80
	s_nop 1
	v_cndmask_b32_e32 v72, v202, v72, vcc
	v_cmp_le_i32_e32 vcc, 17, v80
	s_nop 1
	v_cndmask_b32_e32 v73, v202, v73, vcc
	v_cmp_le_i32_e32 vcc, 18, v80
	s_nop 1
	v_cndmask_b32_e32 v74, v202, v74, vcc
	v_cmp_le_i32_e32 vcc, 19, v80
	s_nop 1
	v_cndmask_b32_e32 v75, v202, v75, vcc
	v_cmp_le_i32_e32 vcc, 24, v80
	s_nop 1
	v_cndmask_b32_e32 v76, v202, v76, vcc
	v_cmp_le_i32_e32 vcc, 25, v80
	s_nop 1
	v_cndmask_b32_e32 v77, v202, v77, vcc
	v_cmp_le_i32_e32 vcc, 26, v80
	s_nop 1
	v_cndmask_b32_e32 v78, v202, v78, vcc
	v_cmp_le_i32_e32 vcc, 27, v80
	s_nop 1
	v_cndmask_b32_e32 v79, v202, v79, vcc
	v_cmp_le_i32_e32 vcc, 32, v80
	s_nop 1
	v_cndmask_b32_e32 v112, v202, v112, vcc
	v_cmp_le_i32_e32 vcc, 33, v80
	s_nop 1
	v_cndmask_b32_e32 v113, v202, v113, vcc
	v_cmp_le_i32_e32 vcc, 34, v80
	s_nop 1
	v_cndmask_b32_e32 v114, v202, v114, vcc
	v_cmp_le_i32_e32 vcc, 35, v80
	s_nop 1
	v_cndmask_b32_e32 v115, v202, v115, vcc
	v_cmp_le_i32_e32 vcc, 40, v80
	s_nop 1
	v_cndmask_b32_e32 v116, v202, v116, vcc
	v_cmp_le_i32_e32 vcc, 41, v80
	s_nop 1
	v_cndmask_b32_e32 v117, v202, v117, vcc
	v_cmp_le_i32_e32 vcc, 42, v80
	s_nop 1
	v_cndmask_b32_e32 v118, v202, v118, vcc
	v_cmp_le_i32_e32 vcc, 43, v80
	s_nop 1
	v_cndmask_b32_e32 v119, v202, v119, vcc
	v_cmp_le_i32_e32 vcc, 48, v80
	s_nop 1
	v_cndmask_b32_e32 v120, v202, v120, vcc
	v_cmp_le_i32_e32 vcc, 49, v80
	s_nop 1
	v_cndmask_b32_e32 v121, v202, v121, vcc
	v_cmp_le_i32_e32 vcc, 50, v80
	s_nop 1
	v_cndmask_b32_e32 v122, v202, v122, vcc
	v_cmp_le_i32_e32 vcc, 51, v80
	s_nop 1
	v_cndmask_b32_e32 v123, v202, v123, vcc
	v_cmp_le_i32_e32 vcc, 56, v80
	s_nop 1
	v_cndmask_b32_e32 v124, v202, v124, vcc
	v_cmp_le_i32_e32 vcc, 57, v80
	s_nop 1
	v_cndmask_b32_e32 v125, v202, v125, vcc
	v_cmp_le_i32_e32 vcc, 58, v80
	s_nop 1
	v_cndmask_b32_e32 v126, v202, v126, vcc
	v_cmp_le_i32_e32 vcc, 59, v80
	s_nop 1
	v_cndmask_b32_e32 v127, v202, v127, vcc
	.p2align 6

.LBB0_646:
.LBB0_647:
	s_load_dwordx2 s[0:1], s[4:5], 0x70
	v_lshlrev_b64 v[2:3], 2, v[0:1]
	s_add_u32 s10, s78, 0x3ae80000
	s_addc_u32 s11, s79, 0
	s_waitcnt lgkmcnt(0)
	v_lshl_add_u64 v[4:5], s[0:1], 0, v[2:3]
	global_load_dword v6, v[4:5], off
	s_nop 0
	global_load_dword v4, v[4:5], off offset:2048
	s_mov_b32 s0, 0x3fb8aa3b
	v_lshl_add_u64 v[2:3], s[10:11], 0, v[2:3]
	global_store_dword v[2:3], v197, off
	s_waitcnt vmcnt(0)
	v_sub_f32_e32 v4, v6, v4
	v_mul_f32_e32 v5, 0x3fb8aa3b, v4
	v_fma_f32 v6, v4, s0, -v5
	v_rndne_f32_e32 v7, v5
	v_fmac_f32_e32 v6, 0x32a5705f, v4
	v_sub_f32_e32 v5, v5, v7
	v_add_f32_e32 v5, v5, v6
	v_cvt_i32_f32_e32 v7, v7
	v_exp_f32_e32 v5, v5
	s_mov_b32 s0, 0xc2ce8ed0
	v_cmp_ngt_f32_e32 vcc, s0, v4
	s_mov_b32 s0, 0x42b17218
	v_ldexp_f32 v5, v5, v7
	v_cndmask_b32_e32 v5, 0, v5, vcc
	v_cmp_nlt_f32_e32 vcc, s0, v4
	s_nop 1
	v_cndmask_b32_e32 v4, v206, v5, vcc
	v_add_f32_e32 v4, 1.0, v4
	v_div_scale_f32 v5, s[0:1], v4, v4, 1.0
	v_rcp_f32_e32 v6, v5
	v_div_scale_f32 v7, vcc, 1.0, v4, 1.0
	s_movk_i32 s0, 0x204
	v_fma_f32 v8, -v5, v6, 1.0
	v_fmac_f32_e32 v6, v8, v6
	v_mul_f32_e32 v8, v7, v6
	v_fma_f32 v9, -v5, v8, v7
	v_fmac_f32_e32 v8, v9, v6
	v_fma_f32 v5, -v5, v8, v7
	v_div_fmas_f32 v5, v5, v6, v8
	v_div_fixup_f32 v4, v5, v4, 1.0
	v_max_f32_e32 v4, 0xda24260, v4
	v_cmp_gt_f32_e32 vcc, s75, v4
	s_nop 1
	v_cndmask_b32_e64 v5, 0, 32, vcc
	v_ldexp_f32 v4, v4, v5
	v_log_f32_e32 v4, v4
	v_cndmask_b32_e32 v5, 0, v204, vcc
	v_mul_f32_e32 v6, 0x3f317217, v4
	v_fma_f32 v6, v4, s92, -v6
	v_fmac_f32_e32 v6, 0x3377d1cf, v4
	v_fmac_f32_e32 v6, 0x3f317217, v4
	v_cmp_lt_f32_e64 vcc, |v4|, s93
	s_nop 1
	v_cndmask_b32_e32 v4, v4, v6, vcc
	v_sub_f32_e32 v4, v4, v5
	v_cmp_gt_i32_e32 vcc, s0, v0
	global_store_dword v[2:3], v4, off offset:2048
	s_and_saveexec_b64 s[12:13], vcc
	s_cbranch_execz .LBB0_652
	s_mov_b64 s[14:15], 0
	v_mov_b32_e32 v4, v0
	s_branch .LBB0_650
	.p2align 6

.LBB0_652:
	s_or_b64 exec, exec, s[12:13]
	v_cmp_gt_i32_e32 vcc, 2, v0
	s_and_saveexec_b64 s[10:11], vcc
	s_cbranch_execz .LBB0_656
	s_load_dwordx2 s[0:1], s[4:5], 0x40
	v_lshlrev_b32_e32 v6, 8, v0
	v_mov_b32_e32 v4, 0
	v_ashrrev_i32_e32 v7, 31, v6
	s_mov_b64 s[12:13], 0
	s_waitcnt lgkmcnt(0)
	v_lshl_add_u64 v[6:7], v[6:7], 2, s[0:1]
	v_mov_b32_e32 v5, v4
	.p2align 6

.LBB0_657:
	s_ashr_i32 s9, s8, 31
	s_lshl_b64 s[0:1], s[8:9], 9
	v_lshl_add_u64 v[2:3], v[0:1], 0, s[0:1]
	s_mov_b64 s[0:1], 0x200000
	v_cmp_gt_u64_e32 vcc, s[0:1], v[2:3]
	s_and_saveexec_b64 s[10:11], vcc
	s_cbranch_execz .LBB0_660
	v_and_b32_e32 v4, 63, v0
	v_lshlrev_b32_e32 v4, 3, v4
	global_load_dwordx2 v[4:5], v4, s[4:5] offset:200
	s_lshl_b64 s[0:1], s[8:9], 12
	s_add_u32 s0, s78, s0
	s_addc_u32 s1, s79, s1
	v_lshl_add_u64 v[0:1], v[0:1], 3, s[0:1]
	s_mov_b64 s[0:1], 0x39e00000
	v_lshl_add_u64 v[0:1], v[0:1], 0, s[0:1]
	s_mov_b64 s[8:9], 0
	.p2align 6

.LBB0_660:
	s_or_b64 exec, exec, s[10:11]
	s_load_dword s0, s[56:57], 0x10
	s_load_dword s8, s[56:57], 0x0
	s_mov_b32 s16, s2
	v_mov_b32_e32 v4, v163
	s_waitcnt lgkmcnt(0)
	s_lshr_b32 s0, s0, 16
	s_cmp_lg_u32 s0, 0
	s_cselect_b64 s[0:1], -1, 0
	s_cmp_lg_u64 s[0:1], 0
	s_addc_u32 s8, s8, 0
	s_ashr_i32 s17, s16, 31
	s_lshl_b64 s[0:1], s[16:17], 12
	v_ashrrev_i32_e32 v5, 31, v4
	s_mov_b32 s9, s85
	v_lshl_add_u64 v[0:1], v[4:5], 3, s[0:1]
	s_mov_b64 s[0:1], 0x4000000
	s_lshl_b64 s[10:11], s[8:9], 12
	v_cmp_gt_u64_e32 vcc, s[0:1], v[0:1]
	s_and_saveexec_b64 s[12:13], vcc
	s_cbranch_execz .LBB0_663
	s_load_dwordx2 s[0:1], s[4:5], 0x0
	s_lshl_b64 s[14:15], s[16:17], 14
	v_lshlrev_b64 v[2:3], 5, v[4:5]
	s_mov_b64 s[18:19], 0
	s_waitcnt lgkmcnt(0)
	s_add_u32 s0, s0, s14
	s_addc_u32 s1, s1, s15
	s_lshl_b64 s[14:15], s[8:9], 14
	s_lshl_b64 s[16:17], s[16:17], 13
	v_lshl_add_u64 v[2:3], s[0:1], 0, v[2:3]
	v_readlane_b32 s0, v255, 34
	v_readlane_b32 s1, v255, 35
	s_add_u32 s0, s0, s16
	s_addc_u32 s1, s1, s17
	v_lshl_add_u64 v[2:3], v[2:3], 0, 16
	v_lshl_add_u64 v[4:5], v[4:5], 4, s[0:1]
	s_lshl_b64 s[16:17], s[8:9], 13
	.p2align 6

.LBB0_663:
	s_or_b64 exec, exec, s[12:13]
	s_mov_b32 s16, s2
	s_ashr_i32 s17, s16, 31
	v_mov_b32_e32 v4, v163
	s_lshl_b64 s[0:1], s[16:17], 12
	v_ashrrev_i32_e32 v5, 31, v4
	v_lshl_add_u64 v[0:1], v[4:5], 3, s[0:1]
	s_mov_b64 s[0:1], 0x1000000
	v_cmp_gt_u64_e32 vcc, s[0:1], v[0:1]
	s_and_saveexec_b64 s[12:13], vcc
	s_cbranch_execz .LBB0_666
	s_load_dwordx2 s[0:1], s[4:5], 0x8
	s_lshl_b64 s[14:15], s[16:17], 14
	v_lshlrev_b64 v[2:3], 5, v[4:5]
	s_mov_b64 s[18:19], 0
	s_waitcnt lgkmcnt(0)
	s_add_u32 s0, s0, s14
	s_addc_u32 s1, s1, s15
	s_lshl_b64 s[14:15], s[8:9], 14
	s_lshl_b64 s[16:17], s[16:17], 13
	v_lshl_add_u64 v[2:3], s[0:1], 0, v[2:3]
	s_add_u32 s0, s78, s16
	s_addc_u32 s1, s79, s17
	v_lshl_add_u64 v[4:5], v[4:5], 4, s[0:1]
	s_mov_b64 s[0:1], 0x37e00000
	v_lshl_add_u64 v[2:3], v[2:3], 0, 16
	v_lshl_add_u64 v[4:5], v[4:5], 0, s[0:1]
	s_lshl_b64 s[16:17], s[8:9], 13
	.p2align 6

.LBB0_668:
	v_mov_b32_e32 v4, v163
	s_mov_b32 s18, s2
	s_mul_i32 s84, s14, 0x1600000
	s_cmpk_gt_i32 s18, 0x15ff
	s_mul_i32 s37, s14, 0x2c00000
	s_cbranch_scc1 .LBB0_671
	s_add_u32 s16, s78, s37
	s_addc_u32 s17, s79, 0
	s_lshl_b64 s[20:21], s[84:85], 2
	v_ashrrev_i32_e32 v2, 4, v4
	v_lshlrev_b32_e32 v0, 2, v4
	v_ashrrev_i32_e32 v3, 3, v4
	v_lshlrev_b32_e32 v4, 3, v4
	s_waitcnt lgkmcnt(0)
	s_add_u32 s20, s10, s20
	v_and_b32_e32 v5, 60, v0
	v_and_b32_e32 v6, 56, v4
	v_mul_lo_u32 v4, v3, s81
	s_addc_u32 s21, s11, s21
	v_lshlrev_b32_e32 v128, 2, v5
	v_lshl_add_u32 v7, v2, 1, 0
	v_add_u32_e32 v8, 0, v4
	v_lshlrev_b32_e32 v9, 1, v6
	v_mul_u32_u24_e32 v4, 0x90, v5
	v_lshl_add_u64 v[0:1], s[20:21], 0, v[128:129]
	s_lshl_b32 s19, s18, 6
	s_lshl_b32 s20, s8, 6
	v_add_u32_e32 v4, v7, v4
	v_add_u32_e32 v5, v8, v9
	v_lshlrev_b32_e32 v128, 1, v6
	.p2align 6

.LBB0_671:
	v_mov_b32_e32 v4, v163
	s_mov_b32 s20, s2
	s_mul_i32 s16, s14, 0xb00000
	s_cmpk_gt_i32 s20, 0xaff
	s_mov_b32 s17, s85
	s_cbranch_scc1 .LBB0_674
	s_load_dwordx2 s[22:23], s[4:5], 0x20
	s_add_u32 s18, s0, s84
	v_ashrrev_i32_e32 v2, 4, v4
	s_addc_u32 s19, s1, 0
	s_lshl_b64 s[38:39], s[16:17], 2
	v_lshlrev_b32_e32 v0, 2, v4
	v_ashrrev_i32_e32 v3, 3, v4
	v_lshlrev_b32_e32 v4, 3, v4
	s_waitcnt lgkmcnt(0)
	s_add_u32 s22, s22, s38
	v_and_b32_e32 v5, 60, v0
	v_and_b32_e32 v6, 56, v4
	v_mul_lo_u32 v4, v3, s81
	s_addc_u32 s23, s23, s39
	v_lshlrev_b32_e32 v128, 2, v5
	v_lshl_add_u32 v7, v2, 1, 0
	v_add_u32_e32 v8, 0, v4
	v_lshlrev_b32_e32 v9, 1, v6
	v_mul_u32_u24_e32 v4, 0x90, v5
	v_lshl_add_u64 v[0:1], s[22:23], 0, v[128:129]
	s_lshl_b32 s21, s20, 6
	s_lshl_b32 s22, s8, 6
	v_add_u32_e32 v4, v7, v4
	v_add_u32_e32 v5, v8, v9
	v_lshlrev_b32_e32 v128, 1, v6
	.p2align 6

.LBB0_674:
	v_mov_b32_e32 v4, v163
	s_mov_b32 s20, s2
	s_cmpk_gt_i32 s20, 0xcff
	s_cbranch_scc1 .LBB0_677
	s_load_dwordx2 s[22:23], s[4:5], 0x28
	s_mul_i32 s18, s14, 0x1a00000
	s_add_u32 s18, s9, s18
	s_mul_i32 s21, s14, 0x3400000
	s_addc_u32 s19, s24, 0
	v_ashrrev_i32_e32 v2, 4, v4
	v_lshlrev_b32_e32 v0, 2, v4
	v_ashrrev_i32_e32 v3, 3, v4
	v_lshlrev_b32_e32 v4, 3, v4
	s_waitcnt lgkmcnt(0)
	s_add_u32 s22, s22, s21
	v_and_b32_e32 v5, 60, v0
	v_and_b32_e32 v6, 56, v4
	v_mul_lo_u32 v4, v3, s81
	s_addc_u32 s23, s23, 0
	v_lshlrev_b32_e32 v128, 2, v5
	v_lshl_add_u32 v7, v2, 1, 0
	v_add_u32_e32 v8, 0, v4
	v_lshlrev_b32_e32 v9, 1, v6
	v_mul_u32_u24_e32 v4, 0x90, v5
	v_lshl_add_u64 v[0:1], s[22:23], 0, v[128:129]
	s_lshl_b32 s21, s20, 6
	s_lshl_b32 s22, s8, 6
	v_add_u32_e32 v4, v7, v4
	v_add_u32_e32 v5, v8, v9
	v_lshlrev_b32_e32 v128, 1, v6
	.p2align 6

.LBB0_677:
	s_lshl_b64 s[18:19], s[14:15], 22
	s_lshl_b64 s[20:21], s[14:15], 23
	v_mov_b32_e32 v4, v163
	s_mov_b32 s38, s2
	s_cmpk_gt_i32 s38, 0x3ff
	s_cbranch_scc1 .LBB0_680
	s_load_dwordx2 s[40:41], s[4:5], 0x30
	s_add_u32 s22, s25, s20
	v_ashrrev_i32_e32 v2, 4, v4
	s_addc_u32 s23, s26, s21
	s_lshl_b64 s[42:43], s[18:19], 2
	v_lshlrev_b32_e32 v0, 2, v4
	v_ashrrev_i32_e32 v3, 3, v4
	v_lshlrev_b32_e32 v4, 3, v4
	s_waitcnt lgkmcnt(0)
	s_add_u32 s40, s40, s42
	v_and_b32_e32 v5, 60, v0
	v_and_b32_e32 v6, 56, v4
	v_mul_lo_u32 v4, v3, s81
	s_addc_u32 s41, s41, s43
	v_lshlrev_b32_e32 v128, 2, v5
	v_lshl_add_u32 v7, v2, 1, 0
	v_add_u32_e32 v8, 0, v4
	v_lshlrev_b32_e32 v9, 1, v6
	v_mul_u32_u24_e32 v4, 0x90, v5
	v_lshl_add_u64 v[0:1], s[40:41], 0, v[128:129]
	s_lshl_b32 s39, s38, 6
	s_lshl_b32 s40, s8, 6
	v_add_u32_e32 v4, v7, v4
	v_add_u32_e32 v5, v8, v9
	v_lshlrev_b32_e32 v128, 1, v6
	.p2align 6

.LBB0_680:
	v_mov_b32_e32 v4, v163
	s_mov_b32 s38, s2
	s_cmpk_gt_i32 s38, 0x15ff
	s_cbranch_scc1 .LBB0_683
	s_load_dwordx2 s[40:41], s[4:5], 0x80
	s_add_u32 s22, s27, s37
	v_ashrrev_i32_e32 v2, 4, v4
	s_addc_u32 s23, s28, 0
	s_lshl_b64 s[42:43], s[84:85], 2
	v_lshlrev_b32_e32 v0, 2, v4
	v_ashrrev_i32_e32 v3, 3, v4
	v_lshlrev_b32_e32 v4, 3, v4
	s_waitcnt lgkmcnt(0)
	s_add_u32 s40, s40, s42
	v_and_b32_e32 v5, 60, v0
	v_and_b32_e32 v6, 56, v4
	v_mul_lo_u32 v4, v3, s81
	s_addc_u32 s41, s41, s43
	v_lshlrev_b32_e32 v128, 2, v5
	v_lshl_add_u32 v7, v2, 1, 0
	v_add_u32_e32 v8, 0, v4
	v_lshlrev_b32_e32 v9, 1, v6
	v_mul_u32_u24_e32 v4, 0x90, v5
	v_lshl_add_u64 v[0:1], s[40:41], 0, v[128:129]
	s_lshl_b32 s37, s38, 6
	s_lshl_b32 s39, s8, 6
	v_add_u32_e32 v4, v7, v4
	v_add_u32_e32 v5, v8, v9
	v_lshlrev_b32_e32 v128, 1, v6
	.p2align 6

.LBB0_683:
	v_mov_b32_e32 v4, v163
	s_mov_b32 s37, s2
	s_cmpk_gt_i32 s37, 0xaff
	s_cbranch_scc1 .LBB0_686
	s_load_dwordx2 s[38:39], s[4:5], 0x88
	s_add_u32 s22, s29, s84
	v_ashrrev_i32_e32 v2, 4, v4
	s_addc_u32 s23, s30, 0
	s_lshl_b64 s[16:17], s[16:17], 2
	v_lshlrev_b32_e32 v0, 2, v4
	v_ashrrev_i32_e32 v3, 3, v4
	v_lshlrev_b32_e32 v4, 3, v4
	s_waitcnt lgkmcnt(0)
	s_add_u32 s16, s38, s16
	v_and_b32_e32 v5, 60, v0
	v_and_b32_e32 v6, 56, v4
	v_mul_lo_u32 v4, v3, s81
	s_addc_u32 s17, s39, s17
	v_lshlrev_b32_e32 v128, 2, v5
	v_lshl_add_u32 v7, v2, 1, 0
	v_add_u32_e32 v8, 0, v4
	v_lshlrev_b32_e32 v9, 1, v6
	v_mul_u32_u24_e32 v4, 0x90, v5
	v_lshl_add_u64 v[0:1], s[16:17], 0, v[128:129]
	s_lshl_b32 s16, s37, 6
	s_lshl_b32 s17, s8, 6
	v_add_u32_e32 v4, v7, v4
	v_add_u32_e32 v5, v8, v9
	v_lshlrev_b32_e32 v128, 1, v6
	.p2align 6

.LBB0_686:
	v_mov_b32_e32 v4, v163
	s_mov_b32 s22, s2
	s_cmpk_gt_i32 s22, 0x3ff
	s_cbranch_scc1 .LBB0_689
	s_load_dwordx2 s[38:39], s[4:5], 0x90
	s_add_u32 s16, s31, s20
	v_ashrrev_i32_e32 v2, 4, v4
	s_addc_u32 s17, s34, s21
	s_lshl_b64 s[18:19], s[18:19], 2
	v_lshlrev_b32_e32 v0, 2, v4
	v_ashrrev_i32_e32 v3, 3, v4
	v_lshlrev_b32_e32 v4, 3, v4
	s_waitcnt lgkmcnt(0)
	s_add_u32 s18, s38, s18
	v_and_b32_e32 v5, 60, v0
	v_and_b32_e32 v6, 56, v4
	v_mul_lo_u32 v4, v3, s81
	s_addc_u32 s19, s39, s19
	v_lshlrev_b32_e32 v128, 2, v5
	v_lshl_add_u32 v7, v2, 1, 0
	v_add_u32_e32 v8, 0, v4
	v_lshlrev_b32_e32 v9, 1, v6
	v_mul_u32_u24_e32 v4, 0x90, v5
	v_lshl_add_u64 v[0:1], s[18:19], 0, v[128:129]
	s_lshl_b32 s18, s22, 6
	s_lshl_b32 s19, s8, 6
	v_add_u32_e32 v4, v7, v4
	v_add_u32_e32 v5, v8, v9
	v_lshlrev_b32_e32 v128, 1, v6
	.p2align 6

.LBB0_689:
	v_mov_b32_e32 v4, v163
	s_mov_b32 s18, s2
	s_cmpk_gt_i32 s18, 0x7f
	s_cbranch_scc1 .LBB0_667
	s_load_dwordx2 s[20:21], s[4:5], 0x98
	s_lshl_b64 s[16:17], s[14:15], 20
	s_add_u32 s16, s35, s16
	s_addc_u32 s17, s36, s17
	s_lshl_b64 s[14:15], s[14:15], 21
	v_ashrrev_i32_e32 v2, 4, v4
	v_lshlrev_b32_e32 v0, 2, v4
	v_ashrrev_i32_e32 v3, 3, v4
	v_lshlrev_b32_e32 v4, 3, v4
	s_waitcnt lgkmcnt(0)
	s_add_u32 s14, s20, s14
	v_and_b32_e32 v5, 60, v0
	v_and_b32_e32 v6, 56, v4
	v_mul_lo_u32 v4, v3, s81
	s_addc_u32 s15, s21, s15
	v_lshlrev_b32_e32 v128, 2, v5
	v_lshl_add_u32 v7, v2, 1, 0
	v_add_u32_e32 v8, 0, v4
	v_lshlrev_b32_e32 v9, 1, v6
	v_mul_u32_u24_e32 v4, 0x90, v5
	v_lshl_add_u64 v[0:1], s[14:15], 0, v[128:129]
	s_lshl_b32 s14, s18, 6
	s_lshl_b32 s15, s8, 6
	v_add_u32_e32 v4, v7, v4
	v_add_u32_e32 v5, v8, v9
	v_lshlrev_b32_e32 v128, 1, v6
	.p2align 6
